# DV2 finishing loop: 4-row quad transpose (v_cndmask dpp) then one dwordx4 og store per 4 rows instead of four dword stores
# baseline (speedup 1.0000x reference)
; __device__ __forceinline__ void phase_attn(const Params& p, int l, unsigned char* smem) {
;     ...
;             const float g0 = p.subln_g[lane * 2], g1 = p.subln_g[lane * 2 + 1];
; #pragma unroll 8
;             for (int i = 0; i < 32; ++i) {
;                 const int qrow = w * 32 + i;
;                 const float2 a0 = *(const float2*)(blk + (size_t)qrow * 128 + lane * 2);
;                 const float2 a1 = *(const float2*)(blk + (size_t)(256 + qrow) * 128 + lane * 2);
;                 const unsigned zz = *(const unsigned*)(p.sz + (grow0 + qrow) * D + hh * 128 + lane * 2);
.LBB0_330:
	s_waitcnt vmcnt(63) expcnt(7) lgkmcnt(15)
	s_barrier
	v_ashrrev_i32_e32 v22, 1, v234
	v_and_b32_e32 v212, 0xffffffe0, v22
	v_ashrrev_i32_e32 v213, 31, v212
	v_lshlrev_b32_e32 v22, 3, v234
	v_and_b32_e32 v22, 0x1f8, v22
	v_mov_b32_e32 v23, 0
	v_readlane_b32 s14, v253, 40
	v_readlane_b32 s15, v253, 41
	v_readlane_b32 s16, v254, 31
	v_readlane_b32 s17, v254, 32
	v_readlane_b32 s18, v254, 33
	v_readlane_b32 s19, v254, 34
	v_readlane_b32 s20, v254, 44
	v_readlane_b32 s21, v254, 45
	v_and_b32_e32 v24, 63, v234
	v_lshl_add_u64 v[214:215], s[14:15], 0, v[22:23]
	v_lshlrev_b32_e32 v22, 2, v24
	v_lshlrev_b64 v[26:27], 9, v[212:213]
	v_lshl_add_u64 v[218:219], s[16:17], 0, v[22:23]
	v_lshl_add_u64 v[216:217], s[18:19], 0, v[22:23]
	v_lshlrev_b32_e32 v22, 3, v24
	v_add_u32_e32 v28, 0x100, v212
	v_or_b32_e32 v26, v26, v22
	v_ashrrev_i32_e32 v29, 31, v28
	v_lshl_add_u64 v[220:221], s[20:21], 0, v[26:27]
	v_lshlrev_b64 v[28:29], 9, v[28:29]
	v_or_b32_e32 v28, v28, v22
	v_lshl_add_u64 v[222:223], s[20:21], 0, v[28:29]
	global_load_dwordx2 v[2:3], v[214:215], off
	v_readlane_b32 s6, v254, 43
	s_or_b32 s6, s37, s6
	s_and_b64 s[4:5], s[4:5], exec
	v_readlane_b32 s4, v254, 42
	s_cselect_b32 s4, s6, s4
	s_mov_b32 s5, s83
	v_lshl_add_u64 v[4:5], v[212:213], 0, s[4:5]
	v_lshlrev_b64 v[6:7], 11, v[4:5]
	s_lshl_b32 s82, s36, 8
	v_lshl_add_u64 v[4:5], v[216:217], 0, v[6:7]
	v_lshl_add_u64 v[6:7], v[218:219], 0, v[6:7]
	s_mov_b64 s[4:5], 0
	s_movk_i32 s6, 0x2000
	s_mov_b32 s7, 0x800000
	s_movk_i32 s8, 0x1000
	s_movk_i32 s9, 0x3000
	s_mov_b64 s[10:11], 0x1000
	s_mov_b64 s[12:13], 0x8000
	s_mov_b32 s22, 0x55555555
	s_mov_b32 s23, 0x55555555
	s_mov_b32 s24, 0xaaaaaaaa
	s_mov_b32 s25, 0xaaaaaaaa
	s_mov_b32 s26, 0x33333333
	s_mov_b32 s27, 0x33333333
	s_mov_b32 s30, 0xcccccccc
	s_mov_b32 s31, 0xcccccccc
	v_and_b32_e32 v151, 3, v234
	v_mul_u32_u24_e32 v151, 0x7fc, v151
	v_add_co_u32_e32 v4, vcc, v4, v151
	v_addc_co_u32_e32 v5, vcc, 0, v5, vcc
.Ldv2fin_loop:
	v_lshl_add_u64 v[8:9], v[220:221], 0, s[4:5]
	v_lshl_add_u64 v[10:11], v[222:223], 0, s[4:5]
	v_lshl_add_u64 v[112:113], v[6:7], 0, s[82:83]
	v_lshl_add_u64 v[128:129], v[4:5], 0, s[82:83]
	v_lshl_add_u64 v[18:19], v[8:9], 0, s[10:11]
	v_lshl_add_u64 v[20:21], v[10:11], 0, s[10:11]
	v_lshl_add_u64 v[114:115], v[112:113], 0, s[10:11]
	v_lshl_add_u64 v[116:117], v[114:115], 0, s[10:11]
	v_lshl_add_u64 v[118:119], v[116:117], 0, s[10:11]
	v_lshl_add_u64 v[120:121], v[118:119], 0, s[10:11]
	v_lshl_add_u64 v[122:123], v[120:121], 0, s[10:11]
	v_lshl_add_u64 v[124:125], v[122:123], 0, s[10:11]
	v_lshl_add_u64 v[126:127], v[124:125], 0, s[10:11]
	v_lshl_add_u64 v[130:131], v[128:129], 0, s[10:11]
	v_lshl_add_u64 v[132:133], v[130:131], 0, s[10:11]
	v_lshl_add_u64 v[134:135], v[132:133], 0, s[10:11]
	v_lshl_add_u64 v[136:137], v[134:135], 0, s[10:11]
	v_lshl_add_u64 v[138:139], v[136:137], 0, s[10:11]
	v_lshl_add_u64 v[140:141], v[138:139], 0, s[10:11]
	v_lshl_add_u64 v[142:143], v[140:141], 0, s[10:11]
	global_load_dwordx2 v[30:31], v[8:9], off
	global_load_dwordx2 v[32:33], v[10:11], off
	global_load_dword v94, v[112:113], off
	global_load_dwordx2 v[34:35], v[8:9], off offset:512
	global_load_dwordx2 v[36:37], v[10:11], off offset:512
	global_load_dword v95, v[112:113], off offset:2048
	global_load_dwordx2 v[38:39], v[8:9], off offset:1024
	global_load_dwordx2 v[40:41], v[10:11], off offset:1024
	global_load_dword v96, v[114:115], off
	global_load_dwordx2 v[42:43], v[8:9], off offset:1536
	global_load_dwordx2 v[44:45], v[10:11], off offset:1536
	global_load_dword v97, v[114:115], off offset:2048
	global_load_dwordx2 v[46:47], v[8:9], off offset:2048
	global_load_dwordx2 v[48:49], v[10:11], off offset:2048
	global_load_dword v98, v[116:117], off
	global_load_dwordx2 v[50:51], v[8:9], off offset:2560
	global_load_dwordx2 v[52:53], v[10:11], off offset:2560
	global_load_dword v99, v[116:117], off offset:2048
	global_load_dwordx2 v[54:55], v[8:9], off offset:3072
	global_load_dwordx2 v[56:57], v[10:11], off offset:3072
	global_load_dword v100, v[118:119], off
	global_load_dwordx2 v[58:59], v[8:9], off offset:3584
	global_load_dwordx2 v[60:61], v[10:11], off offset:3584
	global_load_dword v101, v[118:119], off offset:2048
	global_load_dwordx2 v[62:63], v[18:19], off
	global_load_dwordx2 v[64:65], v[20:21], off
	global_load_dword v102, v[120:121], off
	global_load_dwordx2 v[66:67], v[18:19], off offset:512
	global_load_dwordx2 v[68:69], v[20:21], off offset:512
	global_load_dword v103, v[120:121], off offset:2048
	global_load_dwordx2 v[70:71], v[18:19], off offset:1024
	global_load_dwordx2 v[72:73], v[20:21], off offset:1024
	global_load_dword v104, v[122:123], off
	global_load_dwordx2 v[74:75], v[18:19], off offset:1536
	global_load_dwordx2 v[76:77], v[20:21], off offset:1536
	global_load_dword v105, v[122:123], off offset:2048
	global_load_dwordx2 v[78:79], v[18:19], off offset:2048
	global_load_dwordx2 v[80:81], v[20:21], off offset:2048
	global_load_dword v106, v[124:125], off
	global_load_dwordx2 v[82:83], v[18:19], off offset:2560
	global_load_dwordx2 v[84:85], v[20:21], off offset:2560
	global_load_dword v107, v[124:125], off offset:2048
	global_load_dwordx2 v[86:87], v[18:19], off offset:3072
	global_load_dwordx2 v[88:89], v[20:21], off offset:3072
	global_load_dword v108, v[126:127], off
	global_load_dwordx2 v[90:91], v[18:19], off offset:3584
	global_load_dwordx2 v[92:93], v[20:21], off offset:3584
	global_load_dword v109, v[126:127], off offset:2048
	s_add_u32 s4, s4, 0x2000
	s_addc_u32 s5, s5, 0
	v_lshl_add_u64 v[4:5], v[4:5], 0, s[12:13]
	v_lshl_add_u64 v[6:7], v[6:7], 0, s[12:13]
	s_waitcnt vmcnt(36)
; __device__ __forceinline__ float wave_sum64(float v) {
;     v += __uint_as_float(__builtin_amdgcn_mov_dpp(__float_as_uint(v), 0xB1, 0xF, 0xF, true));
;     v += __uint_as_float(__builtin_amdgcn_mov_dpp(__float_as_uint(v), 0x4E, 0xF, 0xF, true));
;     v += __uint_as_float(__builtin_amdgcn_mov_dpp(__float_as_uint(v), 0x141, 0xF, 0xF, true));
;     v += __uint_as_float(__builtin_amdgcn_mov_dpp(__float_as_uint(v), 0x140, 0xF, 0xF, true));
;     { auto rr = __builtin_amdgcn_permlane16_swap(__float_as_uint(v), __float_as_uint(v), false, false); v = __uint_as_float(rr[0]) + __uint_as_float(rr[1]); }
;     { auto rr = __builtin_amdgcn_permlane32_swap(__float_as_uint(v), __float_as_uint(v), false, false); v = __uint_as_float(rr[0]) + __uint_as_float(rr[1]); }
;     return v;
; __device__ __forceinline__ void phase_attn(const Params& p, int l, unsigned char* smem) {
;     ...
;                 const float o0 = a0.x - lam * a1.x, o1 = a0.y - lam * a1.y;
;                 float ss = o0 * o0 + o1 * o1;
;                 ss = wave_sum64(ss);
;                 const float rstd = rsqrtf(ss * (1.0f / 128.0f) + EPS) * post;
;                 const float z0 = __uint_as_float(zz << 16), z1 = __uint_as_float(zz & 0xffff0000u);
;                 *(unsigned*)(p.og + (grow0 + qrow) * D + hh * 128 + lane * 2) = pk_bf16(o0 * rstd * g0 * z0, o1 * rstd * g1 * z1);
	v_fma_f32 v31, -v17, v33, v31
	v_fma_f32 v35, -v17, v37, v35
	v_fma_f32 v39, -v17, v41, v39
	v_fma_f32 v43, -v17, v45, v43
	v_fma_f32 v30, -v17, v32, v30
	v_fma_f32 v34, -v17, v36, v34
	v_fma_f32 v38, -v17, v40, v38
	v_fma_f32 v42, -v17, v44, v42
	v_mul_f32_e32 v33, v31, v31
	v_mul_f32_e32 v37, v35, v35
	v_mul_f32_e32 v41, v39, v39
	v_mul_f32_e32 v45, v43, v43
	v_fmac_f32_e32 v33, v30, v30
	v_fmac_f32_e32 v37, v34, v34
	v_fmac_f32_e32 v41, v38, v38
	v_fmac_f32_e32 v45, v42, v42
	v_lshlrev_b32_e32 v32, 16, v94
	v_lshlrev_b32_e32 v36, 16, v95
	v_lshlrev_b32_e32 v40, 16, v96
	v_lshlrev_b32_e32 v44, 16, v97
	v_and_b32_e32 v94, 0xffff0000, v94
	v_and_b32_e32 v95, 0xffff0000, v95
	v_and_b32_e32 v96, 0xffff0000, v96
	v_and_b32_e32 v97, 0xffff0000, v97
	v_add_f32_dpp v33, v33, v33 quad_perm:[1,0,3,2] row_mask:0xf bank_mask:0xf bound_ctrl:1
	v_add_f32_dpp v37, v37, v37 quad_perm:[1,0,3,2] row_mask:0xf bank_mask:0xf bound_ctrl:1
	v_add_f32_dpp v41, v41, v41 quad_perm:[1,0,3,2] row_mask:0xf bank_mask:0xf bound_ctrl:1
	v_add_f32_dpp v45, v45, v45 quad_perm:[1,0,3,2] row_mask:0xf bank_mask:0xf bound_ctrl:1
	v_add_f32_dpp v33, v33, v33 quad_perm:[2,3,0,1] row_mask:0xf bank_mask:0xf bound_ctrl:1
	v_add_f32_dpp v37, v37, v37 quad_perm:[2,3,0,1] row_mask:0xf bank_mask:0xf bound_ctrl:1
	v_add_f32_dpp v41, v41, v41 quad_perm:[2,3,0,1] row_mask:0xf bank_mask:0xf bound_ctrl:1
	v_add_f32_dpp v45, v45, v45 quad_perm:[2,3,0,1] row_mask:0xf bank_mask:0xf bound_ctrl:1
	v_add_f32_dpp v33, v33, v33 row_half_mirror row_mask:0xf bank_mask:0xf bound_ctrl:1
	v_add_f32_dpp v37, v37, v37 row_half_mirror row_mask:0xf bank_mask:0xf bound_ctrl:1
	v_add_f32_dpp v41, v41, v41 row_half_mirror row_mask:0xf bank_mask:0xf bound_ctrl:1
	v_add_f32_dpp v45, v45, v45 row_half_mirror row_mask:0xf bank_mask:0xf bound_ctrl:1
	v_add_f32_dpp v33, v33, v33 row_mirror row_mask:0xf bank_mask:0xf bound_ctrl:1
	v_add_f32_dpp v37, v37, v37 row_mirror row_mask:0xf bank_mask:0xf bound_ctrl:1
	v_add_f32_dpp v41, v41, v41 row_mirror row_mask:0xf bank_mask:0xf bound_ctrl:1
	v_add_f32_dpp v45, v45, v45 row_mirror row_mask:0xf bank_mask:0xf bound_ctrl:1
	v_mov_b32_e32 v144, v33
	v_mov_b32_e32 v145, v37
	v_mov_b32_e32 v146, v41
	v_mov_b32_e32 v147, v45
	v_permlane16_swap_b32_e32 v33, v144
	v_permlane16_swap_b32_e32 v37, v145
	v_permlane16_swap_b32_e32 v41, v146
	v_permlane16_swap_b32_e32 v45, v147
	v_add_f32_e32 v33, v33, v144
	v_add_f32_e32 v37, v37, v145
	v_add_f32_e32 v41, v41, v146
	v_add_f32_e32 v45, v45, v147
	v_mov_b32_e32 v144, v33
	v_mov_b32_e32 v145, v37
	v_mov_b32_e32 v146, v41
	v_mov_b32_e32 v147, v45
	v_permlane32_swap_b32_e32 v33, v144
	v_permlane32_swap_b32_e32 v37, v145
	v_permlane32_swap_b32_e32 v41, v146
	v_permlane32_swap_b32_e32 v45, v147
	v_add_f32_e32 v33, v33, v144
	v_add_f32_e32 v37, v37, v145
	v_add_f32_e32 v41, v41, v146
	v_add_f32_e32 v45, v45, v147
	v_fmamk_f32 v33, v33, 0x3c000000, v236
	v_fmamk_f32 v37, v37, 0x3c000000, v236
	v_fmamk_f32 v41, v41, 0x3c000000, v236
	v_fmamk_f32 v45, v45, 0x3c000000, v236
	v_mul_f32_e32 v144, 0x4b800000, v33
	v_mul_f32_e32 v145, 0x4b800000, v37
	v_mul_f32_e32 v146, 0x4b800000, v41
	v_mul_f32_e32 v147, 0x4b800000, v45
	v_cmp_gt_f32_e64 s[14:15], s7, v33
	v_cmp_gt_f32_e64 s[16:17], s7, v37
	v_cmp_gt_f32_e64 s[18:19], s7, v41
	v_cmp_gt_f32_e64 s[20:21], s7, v45
	v_cndmask_b32_e64 v33, v33, v144, s[14:15]
	v_cndmask_b32_e64 v37, v37, v145, s[16:17]
	v_cndmask_b32_e64 v41, v41, v146, s[18:19]
	v_cndmask_b32_e64 v45, v45, v147, s[20:21]
	v_rsq_f32_e32 v33, v33
	v_rsq_f32_e32 v37, v37
	v_rsq_f32_e32 v41, v41
	v_rsq_f32_e32 v45, v45
	v_mul_f32_e32 v144, 0x45800000, v33
	v_mul_f32_e32 v145, 0x45800000, v37
	v_mul_f32_e32 v146, 0x45800000, v41
	v_mul_f32_e32 v147, 0x45800000, v45
	v_cndmask_b32_e64 v33, v33, v144, s[14:15]
	v_cndmask_b32_e64 v37, v37, v145, s[16:17]
	v_cndmask_b32_e64 v41, v41, v146, s[18:19]
	v_cndmask_b32_e64 v45, v45, v147, s[20:21]
	v_mul_f32_e32 v33, v235, v33
	v_mul_f32_e32 v37, v235, v37
	v_mul_f32_e32 v41, v235, v41
	v_mul_f32_e32 v45, v235, v45
	v_mul_f32_e32 v31, v31, v33
	v_mul_f32_e32 v35, v35, v37
	v_mul_f32_e32 v39, v39, v41
	v_mul_f32_e32 v43, v43, v45
	v_mul_f32_e32 v30, v30, v33
	v_mul_f32_e32 v34, v34, v37
	v_mul_f32_e32 v38, v38, v41
	v_mul_f32_e32 v42, v42, v45
	v_mul_f32_e32 v31, v3, v31
	v_mul_f32_e32 v35, v3, v35
	v_mul_f32_e32 v39, v3, v39
	v_mul_f32_e32 v43, v3, v43
	v_mul_f32_e32 v30, v2, v30
	v_mul_f32_e32 v34, v2, v34
	v_mul_f32_e32 v38, v2, v38
	v_mul_f32_e32 v42, v2, v42
	v_mul_f32_e32 v94, v31, v94
	v_mul_f32_e32 v95, v35, v95
	v_mul_f32_e32 v96, v39, v96
	v_mul_f32_e32 v97, v43, v97
	v_mul_f32_e32 v30, v30, v32
	v_mul_f32_e32 v34, v34, v36
	v_mul_f32_e32 v38, v38, v40
	v_mul_f32_e32 v42, v42, v44
	v_cvt_pk_bf16_f32 v94, v30, v94
	v_cvt_pk_bf16_f32 v95, v34, v95
	v_cvt_pk_bf16_f32 v96, v38, v96
	v_cvt_pk_bf16_f32 v97, v42, v97
	s_nop 1
	s_mov_b64 vcc, s[22:23]
	v_cndmask_b32_dpp v148, v95, v94, vcc quad_perm:[1,0,3,2] row_mask:0xf bank_mask:0xf
	v_cndmask_b32_dpp v149, v97, v96, vcc quad_perm:[1,0,3,2] row_mask:0xf bank_mask:0xf
	s_mov_b64 vcc, s[24:25]
	v_cndmask_b32_dpp v150, v94, v95, vcc quad_perm:[1,0,3,2] row_mask:0xf bank_mask:0xf
	v_cndmask_b32_dpp v97, v96, v97, vcc quad_perm:[1,0,3,2] row_mask:0xf bank_mask:0xf
	s_mov_b64 vcc, s[26:27]
	v_cndmask_b32_dpp v94, v149, v148, vcc quad_perm:[2,3,0,1] row_mask:0xf bank_mask:0xf
	v_cndmask_b32_dpp v95, v97, v150, vcc quad_perm:[2,3,0,1] row_mask:0xf bank_mask:0xf
	s_mov_b64 vcc, s[30:31]
	v_cndmask_b32_dpp v96, v148, v149, vcc quad_perm:[2,3,0,1] row_mask:0xf bank_mask:0xf
	v_cndmask_b32_dpp v97, v150, v97, vcc quad_perm:[2,3,0,1] row_mask:0xf bank_mask:0xf
	global_store_dwordx4 v[128:129], v[94:97], off
	s_waitcnt vmcnt(25)
; __device__ __forceinline__ float wave_sum64(float v) {
;     v += __uint_as_float(__builtin_amdgcn_mov_dpp(__float_as_uint(v), 0xB1, 0xF, 0xF, true));
;     v += __uint_as_float(__builtin_amdgcn_mov_dpp(__float_as_uint(v), 0x4E, 0xF, 0xF, true));
;     v += __uint_as_float(__builtin_amdgcn_mov_dpp(__float_as_uint(v), 0x141, 0xF, 0xF, true));
;     v += __uint_as_float(__builtin_amdgcn_mov_dpp(__float_as_uint(v), 0x140, 0xF, 0xF, true));
;     { auto rr = __builtin_amdgcn_permlane16_swap(__float_as_uint(v), __float_as_uint(v), false, false); v = __uint_as_float(rr[0]) + __uint_as_float(rr[1]); }
;     { auto rr = __builtin_amdgcn_permlane32_swap(__float_as_uint(v), __float_as_uint(v), false, false); v = __uint_as_float(rr[0]) + __uint_as_float(rr[1]); }
;     return v;
; __device__ __forceinline__ void phase_attn(const Params& p, int l, unsigned char* smem) {
;     ...
;                 const float o0 = a0.x - lam * a1.x, o1 = a0.y - lam * a1.y;
;                 float ss = o0 * o0 + o1 * o1;
;                 ss = wave_sum64(ss);
;                 const float rstd = rsqrtf(ss * (1.0f / 128.0f) + EPS) * post;
;                 const float z0 = __uint_as_float(zz << 16), z1 = __uint_as_float(zz & 0xffff0000u);
;                 *(unsigned*)(p.og + (grow0 + qrow) * D + hh * 128 + lane * 2) = pk_bf16(o0 * rstd * g0 * z0, o1 * rstd * g1 * z1);
	v_fma_f32 v47, -v17, v49, v47
	v_fma_f32 v51, -v17, v53, v51
	v_fma_f32 v55, -v17, v57, v55
	v_fma_f32 v59, -v17, v61, v59
	v_fma_f32 v46, -v17, v48, v46
	v_fma_f32 v50, -v17, v52, v50
	v_fma_f32 v54, -v17, v56, v54
	v_fma_f32 v58, -v17, v60, v58
	v_mul_f32_e32 v49, v47, v47
	v_mul_f32_e32 v53, v51, v51
	v_mul_f32_e32 v57, v55, v55
	v_mul_f32_e32 v61, v59, v59
	v_fmac_f32_e32 v49, v46, v46
	v_fmac_f32_e32 v53, v50, v50
	v_fmac_f32_e32 v57, v54, v54
	v_fmac_f32_e32 v61, v58, v58
	v_lshlrev_b32_e32 v48, 16, v98
	v_lshlrev_b32_e32 v52, 16, v99
	v_lshlrev_b32_e32 v56, 16, v100
	v_lshlrev_b32_e32 v60, 16, v101
	v_and_b32_e32 v98, 0xffff0000, v98
	v_and_b32_e32 v99, 0xffff0000, v99
	v_and_b32_e32 v100, 0xffff0000, v100
	v_and_b32_e32 v101, 0xffff0000, v101
	v_add_f32_dpp v49, v49, v49 quad_perm:[1,0,3,2] row_mask:0xf bank_mask:0xf bound_ctrl:1
	v_add_f32_dpp v53, v53, v53 quad_perm:[1,0,3,2] row_mask:0xf bank_mask:0xf bound_ctrl:1
	v_add_f32_dpp v57, v57, v57 quad_perm:[1,0,3,2] row_mask:0xf bank_mask:0xf bound_ctrl:1
	v_add_f32_dpp v61, v61, v61 quad_perm:[1,0,3,2] row_mask:0xf bank_mask:0xf bound_ctrl:1
	v_add_f32_dpp v49, v49, v49 quad_perm:[2,3,0,1] row_mask:0xf bank_mask:0xf bound_ctrl:1
	v_add_f32_dpp v53, v53, v53 quad_perm:[2,3,0,1] row_mask:0xf bank_mask:0xf bound_ctrl:1
	v_add_f32_dpp v57, v57, v57 quad_perm:[2,3,0,1] row_mask:0xf bank_mask:0xf bound_ctrl:1
	v_add_f32_dpp v61, v61, v61 quad_perm:[2,3,0,1] row_mask:0xf bank_mask:0xf bound_ctrl:1
	v_add_f32_dpp v49, v49, v49 row_half_mirror row_mask:0xf bank_mask:0xf bound_ctrl:1
	v_add_f32_dpp v53, v53, v53 row_half_mirror row_mask:0xf bank_mask:0xf bound_ctrl:1
	v_add_f32_dpp v57, v57, v57 row_half_mirror row_mask:0xf bank_mask:0xf bound_ctrl:1
	v_add_f32_dpp v61, v61, v61 row_half_mirror row_mask:0xf bank_mask:0xf bound_ctrl:1
	v_add_f32_dpp v49, v49, v49 row_mirror row_mask:0xf bank_mask:0xf bound_ctrl:1
	v_add_f32_dpp v53, v53, v53 row_mirror row_mask:0xf bank_mask:0xf bound_ctrl:1
	v_add_f32_dpp v57, v57, v57 row_mirror row_mask:0xf bank_mask:0xf bound_ctrl:1
	v_add_f32_dpp v61, v61, v61 row_mirror row_mask:0xf bank_mask:0xf bound_ctrl:1
	v_mov_b32_e32 v144, v49
	v_mov_b32_e32 v145, v53
	v_mov_b32_e32 v146, v57
	v_mov_b32_e32 v147, v61
	v_permlane16_swap_b32_e32 v49, v144
	v_permlane16_swap_b32_e32 v53, v145
	v_permlane16_swap_b32_e32 v57, v146
	v_permlane16_swap_b32_e32 v61, v147
	v_add_f32_e32 v49, v49, v144
	v_add_f32_e32 v53, v53, v145
	v_add_f32_e32 v57, v57, v146
	v_add_f32_e32 v61, v61, v147
	v_mov_b32_e32 v144, v49
	v_mov_b32_e32 v145, v53
	v_mov_b32_e32 v146, v57
	v_mov_b32_e32 v147, v61
	v_permlane32_swap_b32_e32 v49, v144
	v_permlane32_swap_b32_e32 v53, v145
	v_permlane32_swap_b32_e32 v57, v146
	v_permlane32_swap_b32_e32 v61, v147
	v_add_f32_e32 v49, v49, v144
	v_add_f32_e32 v53, v53, v145
	v_add_f32_e32 v57, v57, v146
	v_add_f32_e32 v61, v61, v147
	v_fmamk_f32 v49, v49, 0x3c000000, v236
	v_fmamk_f32 v53, v53, 0x3c000000, v236
	v_fmamk_f32 v57, v57, 0x3c000000, v236
	v_fmamk_f32 v61, v61, 0x3c000000, v236
	v_mul_f32_e32 v144, 0x4b800000, v49
	v_mul_f32_e32 v145, 0x4b800000, v53
	v_mul_f32_e32 v146, 0x4b800000, v57
	v_mul_f32_e32 v147, 0x4b800000, v61
	v_cmp_gt_f32_e64 s[14:15], s7, v49
	v_cmp_gt_f32_e64 s[16:17], s7, v53
	v_cmp_gt_f32_e64 s[18:19], s7, v57
	v_cmp_gt_f32_e64 s[20:21], s7, v61
	v_cndmask_b32_e64 v49, v49, v144, s[14:15]
	v_cndmask_b32_e64 v53, v53, v145, s[16:17]
	v_cndmask_b32_e64 v57, v57, v146, s[18:19]
	v_cndmask_b32_e64 v61, v61, v147, s[20:21]
	v_rsq_f32_e32 v49, v49
	v_rsq_f32_e32 v53, v53
	v_rsq_f32_e32 v57, v57
	v_rsq_f32_e32 v61, v61
	v_mul_f32_e32 v144, 0x45800000, v49
	v_mul_f32_e32 v145, 0x45800000, v53
	v_mul_f32_e32 v146, 0x45800000, v57
	v_mul_f32_e32 v147, 0x45800000, v61
	v_cndmask_b32_e64 v49, v49, v144, s[14:15]
	v_cndmask_b32_e64 v53, v53, v145, s[16:17]
	v_cndmask_b32_e64 v57, v57, v146, s[18:19]
	v_cndmask_b32_e64 v61, v61, v147, s[20:21]
	v_mul_f32_e32 v49, v235, v49
	v_mul_f32_e32 v53, v235, v53
	v_mul_f32_e32 v57, v235, v57
	v_mul_f32_e32 v61, v235, v61
	v_mul_f32_e32 v47, v47, v49
	v_mul_f32_e32 v51, v51, v53
	v_mul_f32_e32 v55, v55, v57
	v_mul_f32_e32 v59, v59, v61
	v_mul_f32_e32 v46, v46, v49
	v_mul_f32_e32 v50, v50, v53
	v_mul_f32_e32 v54, v54, v57
	v_mul_f32_e32 v58, v58, v61
	v_mul_f32_e32 v47, v3, v47
	v_mul_f32_e32 v51, v3, v51
	v_mul_f32_e32 v55, v3, v55
	v_mul_f32_e32 v59, v3, v59
	v_mul_f32_e32 v46, v2, v46
	v_mul_f32_e32 v50, v2, v50
	v_mul_f32_e32 v54, v2, v54
	v_mul_f32_e32 v58, v2, v58
	v_mul_f32_e32 v98, v47, v98
	v_mul_f32_e32 v99, v51, v99
	v_mul_f32_e32 v100, v55, v100
	v_mul_f32_e32 v101, v59, v101
	v_mul_f32_e32 v46, v46, v48
	v_mul_f32_e32 v50, v50, v52
	v_mul_f32_e32 v54, v54, v56
	v_mul_f32_e32 v58, v58, v60
	v_cvt_pk_bf16_f32 v98, v46, v98
	v_cvt_pk_bf16_f32 v99, v50, v99
	v_cvt_pk_bf16_f32 v100, v54, v100
	v_cvt_pk_bf16_f32 v101, v58, v101
	s_nop 1
	s_mov_b64 vcc, s[22:23]
	v_cndmask_b32_dpp v148, v99, v98, vcc quad_perm:[1,0,3,2] row_mask:0xf bank_mask:0xf
	v_cndmask_b32_dpp v149, v101, v100, vcc quad_perm:[1,0,3,2] row_mask:0xf bank_mask:0xf
	s_mov_b64 vcc, s[24:25]
	v_cndmask_b32_dpp v150, v98, v99, vcc quad_perm:[1,0,3,2] row_mask:0xf bank_mask:0xf
	v_cndmask_b32_dpp v101, v100, v101, vcc quad_perm:[1,0,3,2] row_mask:0xf bank_mask:0xf
	s_mov_b64 vcc, s[26:27]
	v_cndmask_b32_dpp v98, v149, v148, vcc quad_perm:[2,3,0,1] row_mask:0xf bank_mask:0xf
	v_cndmask_b32_dpp v99, v101, v150, vcc quad_perm:[2,3,0,1] row_mask:0xf bank_mask:0xf
	s_mov_b64 vcc, s[30:31]
	v_cndmask_b32_dpp v100, v148, v149, vcc quad_perm:[2,3,0,1] row_mask:0xf bank_mask:0xf
	v_cndmask_b32_dpp v101, v150, v101, vcc quad_perm:[2,3,0,1] row_mask:0xf bank_mask:0xf
	global_store_dwordx4 v[132:133], v[98:101], off
	s_waitcnt vmcnt(14)
; __device__ __forceinline__ float wave_sum64(float v) {
;     v += __uint_as_float(__builtin_amdgcn_mov_dpp(__float_as_uint(v), 0xB1, 0xF, 0xF, true));
;     v += __uint_as_float(__builtin_amdgcn_mov_dpp(__float_as_uint(v), 0x4E, 0xF, 0xF, true));
;     v += __uint_as_float(__builtin_amdgcn_mov_dpp(__float_as_uint(v), 0x141, 0xF, 0xF, true));
;     v += __uint_as_float(__builtin_amdgcn_mov_dpp(__float_as_uint(v), 0x140, 0xF, 0xF, true));
;     { auto rr = __builtin_amdgcn_permlane16_swap(__float_as_uint(v), __float_as_uint(v), false, false); v = __uint_as_float(rr[0]) + __uint_as_float(rr[1]); }
;     { auto rr = __builtin_amdgcn_permlane32_swap(__float_as_uint(v), __float_as_uint(v), false, false); v = __uint_as_float(rr[0]) + __uint_as_float(rr[1]); }
;     return v;
; __device__ __forceinline__ void phase_attn(const Params& p, int l, unsigned char* smem) {
;     ...
;                 const float o0 = a0.x - lam * a1.x, o1 = a0.y - lam * a1.y;
;                 float ss = o0 * o0 + o1 * o1;
;                 ss = wave_sum64(ss);
;                 const float rstd = rsqrtf(ss * (1.0f / 128.0f) + EPS) * post;
;                 const float z0 = __uint_as_float(zz << 16), z1 = __uint_as_float(zz & 0xffff0000u);
;                 *(unsigned*)(p.og + (grow0 + qrow) * D + hh * 128 + lane * 2) = pk_bf16(o0 * rstd * g0 * z0, o1 * rstd * g1 * z1);
	v_fma_f32 v63, -v17, v65, v63
	v_fma_f32 v67, -v17, v69, v67
	v_fma_f32 v71, -v17, v73, v71
	v_fma_f32 v75, -v17, v77, v75
	v_fma_f32 v62, -v17, v64, v62
	v_fma_f32 v66, -v17, v68, v66
	v_fma_f32 v70, -v17, v72, v70
	v_fma_f32 v74, -v17, v76, v74
	v_mul_f32_e32 v65, v63, v63
	v_mul_f32_e32 v69, v67, v67
	v_mul_f32_e32 v73, v71, v71
	v_mul_f32_e32 v77, v75, v75
	v_fmac_f32_e32 v65, v62, v62
	v_fmac_f32_e32 v69, v66, v66
	v_fmac_f32_e32 v73, v70, v70
	v_fmac_f32_e32 v77, v74, v74
	v_lshlrev_b32_e32 v64, 16, v102
	v_lshlrev_b32_e32 v68, 16, v103
	v_lshlrev_b32_e32 v72, 16, v104
	v_lshlrev_b32_e32 v76, 16, v105
	v_and_b32_e32 v102, 0xffff0000, v102
	v_and_b32_e32 v103, 0xffff0000, v103
	v_and_b32_e32 v104, 0xffff0000, v104
	v_and_b32_e32 v105, 0xffff0000, v105
	v_add_f32_dpp v65, v65, v65 quad_perm:[1,0,3,2] row_mask:0xf bank_mask:0xf bound_ctrl:1
	v_add_f32_dpp v69, v69, v69 quad_perm:[1,0,3,2] row_mask:0xf bank_mask:0xf bound_ctrl:1
	v_add_f32_dpp v73, v73, v73 quad_perm:[1,0,3,2] row_mask:0xf bank_mask:0xf bound_ctrl:1
	v_add_f32_dpp v77, v77, v77 quad_perm:[1,0,3,2] row_mask:0xf bank_mask:0xf bound_ctrl:1
	v_add_f32_dpp v65, v65, v65 quad_perm:[2,3,0,1] row_mask:0xf bank_mask:0xf bound_ctrl:1
	v_add_f32_dpp v69, v69, v69 quad_perm:[2,3,0,1] row_mask:0xf bank_mask:0xf bound_ctrl:1
	v_add_f32_dpp v73, v73, v73 quad_perm:[2,3,0,1] row_mask:0xf bank_mask:0xf bound_ctrl:1
	v_add_f32_dpp v77, v77, v77 quad_perm:[2,3,0,1] row_mask:0xf bank_mask:0xf bound_ctrl:1
	v_add_f32_dpp v65, v65, v65 row_half_mirror row_mask:0xf bank_mask:0xf bound_ctrl:1
	v_add_f32_dpp v69, v69, v69 row_half_mirror row_mask:0xf bank_mask:0xf bound_ctrl:1
	v_add_f32_dpp v73, v73, v73 row_half_mirror row_mask:0xf bank_mask:0xf bound_ctrl:1
	v_add_f32_dpp v77, v77, v77 row_half_mirror row_mask:0xf bank_mask:0xf bound_ctrl:1
	v_add_f32_dpp v65, v65, v65 row_mirror row_mask:0xf bank_mask:0xf bound_ctrl:1
	v_add_f32_dpp v69, v69, v69 row_mirror row_mask:0xf bank_mask:0xf bound_ctrl:1
	v_add_f32_dpp v73, v73, v73 row_mirror row_mask:0xf bank_mask:0xf bound_ctrl:1
	v_add_f32_dpp v77, v77, v77 row_mirror row_mask:0xf bank_mask:0xf bound_ctrl:1
	v_mov_b32_e32 v144, v65
	v_mov_b32_e32 v145, v69
	v_mov_b32_e32 v146, v73
	v_mov_b32_e32 v147, v77
	v_permlane16_swap_b32_e32 v65, v144
	v_permlane16_swap_b32_e32 v69, v145
	v_permlane16_swap_b32_e32 v73, v146
	v_permlane16_swap_b32_e32 v77, v147
	v_add_f32_e32 v65, v65, v144
	v_add_f32_e32 v69, v69, v145
	v_add_f32_e32 v73, v73, v146
	v_add_f32_e32 v77, v77, v147
	v_mov_b32_e32 v144, v65
	v_mov_b32_e32 v145, v69
	v_mov_b32_e32 v146, v73
	v_mov_b32_e32 v147, v77
	v_permlane32_swap_b32_e32 v65, v144
	v_permlane32_swap_b32_e32 v69, v145
	v_permlane32_swap_b32_e32 v73, v146
	v_permlane32_swap_b32_e32 v77, v147
	v_add_f32_e32 v65, v65, v144
	v_add_f32_e32 v69, v69, v145
	v_add_f32_e32 v73, v73, v146
	v_add_f32_e32 v77, v77, v147
	v_fmamk_f32 v65, v65, 0x3c000000, v236
	v_fmamk_f32 v69, v69, 0x3c000000, v236
	v_fmamk_f32 v73, v73, 0x3c000000, v236
	v_fmamk_f32 v77, v77, 0x3c000000, v236
	v_mul_f32_e32 v144, 0x4b800000, v65
	v_mul_f32_e32 v145, 0x4b800000, v69
	v_mul_f32_e32 v146, 0x4b800000, v73
	v_mul_f32_e32 v147, 0x4b800000, v77
	v_cmp_gt_f32_e64 s[14:15], s7, v65
	v_cmp_gt_f32_e64 s[16:17], s7, v69
	v_cmp_gt_f32_e64 s[18:19], s7, v73
	v_cmp_gt_f32_e64 s[20:21], s7, v77
	v_cndmask_b32_e64 v65, v65, v144, s[14:15]
	v_cndmask_b32_e64 v69, v69, v145, s[16:17]
	v_cndmask_b32_e64 v73, v73, v146, s[18:19]
	v_cndmask_b32_e64 v77, v77, v147, s[20:21]
	v_rsq_f32_e32 v65, v65
	v_rsq_f32_e32 v69, v69
	v_rsq_f32_e32 v73, v73
	v_rsq_f32_e32 v77, v77
	v_mul_f32_e32 v144, 0x45800000, v65
	v_mul_f32_e32 v145, 0x45800000, v69
	v_mul_f32_e32 v146, 0x45800000, v73
	v_mul_f32_e32 v147, 0x45800000, v77
	v_cndmask_b32_e64 v65, v65, v144, s[14:15]
	v_cndmask_b32_e64 v69, v69, v145, s[16:17]
	v_cndmask_b32_e64 v73, v73, v146, s[18:19]
	v_cndmask_b32_e64 v77, v77, v147, s[20:21]
	v_mul_f32_e32 v65, v235, v65
	v_mul_f32_e32 v69, v235, v69
	v_mul_f32_e32 v73, v235, v73
	v_mul_f32_e32 v77, v235, v77
	v_mul_f32_e32 v63, v63, v65
	v_mul_f32_e32 v67, v67, v69
	v_mul_f32_e32 v71, v71, v73
	v_mul_f32_e32 v75, v75, v77
	v_mul_f32_e32 v62, v62, v65
	v_mul_f32_e32 v66, v66, v69
	v_mul_f32_e32 v70, v70, v73
	v_mul_f32_e32 v74, v74, v77
	v_mul_f32_e32 v63, v3, v63
	v_mul_f32_e32 v67, v3, v67
	v_mul_f32_e32 v71, v3, v71
	v_mul_f32_e32 v75, v3, v75
	v_mul_f32_e32 v62, v2, v62
	v_mul_f32_e32 v66, v2, v66
	v_mul_f32_e32 v70, v2, v70
	v_mul_f32_e32 v74, v2, v74
	v_mul_f32_e32 v102, v63, v102
	v_mul_f32_e32 v103, v67, v103
	v_mul_f32_e32 v104, v71, v104
	v_mul_f32_e32 v105, v75, v105
	v_mul_f32_e32 v62, v62, v64
	v_mul_f32_e32 v66, v66, v68
	v_mul_f32_e32 v70, v70, v72
	v_mul_f32_e32 v74, v74, v76
	v_cvt_pk_bf16_f32 v102, v62, v102
	v_cvt_pk_bf16_f32 v103, v66, v103
	v_cvt_pk_bf16_f32 v104, v70, v104
	v_cvt_pk_bf16_f32 v105, v74, v105
	s_nop 1
	s_mov_b64 vcc, s[22:23]
	v_cndmask_b32_dpp v148, v103, v102, vcc quad_perm:[1,0,3,2] row_mask:0xf bank_mask:0xf
	v_cndmask_b32_dpp v149, v105, v104, vcc quad_perm:[1,0,3,2] row_mask:0xf bank_mask:0xf
	s_mov_b64 vcc, s[24:25]
	v_cndmask_b32_dpp v150, v102, v103, vcc quad_perm:[1,0,3,2] row_mask:0xf bank_mask:0xf
	v_cndmask_b32_dpp v105, v104, v105, vcc quad_perm:[1,0,3,2] row_mask:0xf bank_mask:0xf
	s_mov_b64 vcc, s[26:27]
	v_cndmask_b32_dpp v102, v149, v148, vcc quad_perm:[2,3,0,1] row_mask:0xf bank_mask:0xf
	v_cndmask_b32_dpp v103, v105, v150, vcc quad_perm:[2,3,0,1] row_mask:0xf bank_mask:0xf
	s_mov_b64 vcc, s[30:31]
	v_cndmask_b32_dpp v104, v148, v149, vcc quad_perm:[2,3,0,1] row_mask:0xf bank_mask:0xf
	v_cndmask_b32_dpp v105, v150, v105, vcc quad_perm:[2,3,0,1] row_mask:0xf bank_mask:0xf
	global_store_dwordx4 v[136:137], v[102:105], off
	s_waitcnt vmcnt(3)
; __device__ __forceinline__ void phase_attn(const Params& p, int l, unsigned char* smem) {
;     ...
;                 const float o0 = a0.x - lam * a1.x, o1 = a0.y - lam * a1.y;
;                 float ss = o0 * o0 + o1 * o1;
;                 ss = wave_sum64(ss);
;                 const float rstd = rsqrtf(ss * (1.0f / 128.0f) + EPS) * post;
;                 const float z0 = __uint_as_float(zz << 16), z1 = __uint_as_float(zz & 0xffff0000u);
;                 *(unsigned*)(p.og + (grow0 + qrow) * D + hh * 128 + lane * 2) = pk_bf16(o0 * rstd * g0 * z0, o1 * rstd * g1 * z1);
;             }
;             __syncthreads();
;         }
	v_fma_f32 v79, -v17, v81, v79
	v_fma_f32 v83, -v17, v85, v83
	v_fma_f32 v87, -v17, v89, v87
	v_fma_f32 v91, -v17, v93, v91
	v_fma_f32 v78, -v17, v80, v78
	v_fma_f32 v82, -v17, v84, v82
	v_fma_f32 v86, -v17, v88, v86
	v_fma_f32 v90, -v17, v92, v90
	v_mul_f32_e32 v81, v79, v79
	v_mul_f32_e32 v85, v83, v83
	v_mul_f32_e32 v89, v87, v87
	v_mul_f32_e32 v93, v91, v91
	v_fmac_f32_e32 v81, v78, v78
	v_fmac_f32_e32 v85, v82, v82
	v_fmac_f32_e32 v89, v86, v86
	v_fmac_f32_e32 v93, v90, v90
	v_lshlrev_b32_e32 v80, 16, v106
	v_lshlrev_b32_e32 v84, 16, v107
	v_lshlrev_b32_e32 v88, 16, v108
	v_lshlrev_b32_e32 v92, 16, v109
	v_and_b32_e32 v106, 0xffff0000, v106
	v_and_b32_e32 v107, 0xffff0000, v107
	v_and_b32_e32 v108, 0xffff0000, v108
	v_and_b32_e32 v109, 0xffff0000, v109
	v_add_f32_dpp v81, v81, v81 quad_perm:[1,0,3,2] row_mask:0xf bank_mask:0xf bound_ctrl:1
	v_add_f32_dpp v85, v85, v85 quad_perm:[1,0,3,2] row_mask:0xf bank_mask:0xf bound_ctrl:1
	v_add_f32_dpp v89, v89, v89 quad_perm:[1,0,3,2] row_mask:0xf bank_mask:0xf bound_ctrl:1
	v_add_f32_dpp v93, v93, v93 quad_perm:[1,0,3,2] row_mask:0xf bank_mask:0xf bound_ctrl:1
	v_add_f32_dpp v81, v81, v81 quad_perm:[2,3,0,1] row_mask:0xf bank_mask:0xf bound_ctrl:1
	v_add_f32_dpp v85, v85, v85 quad_perm:[2,3,0,1] row_mask:0xf bank_mask:0xf bound_ctrl:1
	v_add_f32_dpp v89, v89, v89 quad_perm:[2,3,0,1] row_mask:0xf bank_mask:0xf bound_ctrl:1
	v_add_f32_dpp v93, v93, v93 quad_perm:[2,3,0,1] row_mask:0xf bank_mask:0xf bound_ctrl:1
	v_add_f32_dpp v81, v81, v81 row_half_mirror row_mask:0xf bank_mask:0xf bound_ctrl:1
	v_add_f32_dpp v85, v85, v85 row_half_mirror row_mask:0xf bank_mask:0xf bound_ctrl:1
	v_add_f32_dpp v89, v89, v89 row_half_mirror row_mask:0xf bank_mask:0xf bound_ctrl:1
	v_add_f32_dpp v93, v93, v93 row_half_mirror row_mask:0xf bank_mask:0xf bound_ctrl:1
	v_add_f32_dpp v81, v81, v81 row_mirror row_mask:0xf bank_mask:0xf bound_ctrl:1
	v_add_f32_dpp v85, v85, v85 row_mirror row_mask:0xf bank_mask:0xf bound_ctrl:1
	v_add_f32_dpp v89, v89, v89 row_mirror row_mask:0xf bank_mask:0xf bound_ctrl:1
	v_add_f32_dpp v93, v93, v93 row_mirror row_mask:0xf bank_mask:0xf bound_ctrl:1
	v_mov_b32_e32 v144, v81
	v_mov_b32_e32 v145, v85
	v_mov_b32_e32 v146, v89
	v_mov_b32_e32 v147, v93
	v_permlane16_swap_b32_e32 v81, v144
	v_permlane16_swap_b32_e32 v85, v145
	v_permlane16_swap_b32_e32 v89, v146
	v_permlane16_swap_b32_e32 v93, v147
	v_add_f32_e32 v81, v81, v144
	v_add_f32_e32 v85, v85, v145
	v_add_f32_e32 v89, v89, v146
	v_add_f32_e32 v93, v93, v147
	v_mov_b32_e32 v144, v81
	v_mov_b32_e32 v145, v85
	v_mov_b32_e32 v146, v89
	v_mov_b32_e32 v147, v93
	v_permlane32_swap_b32_e32 v81, v144
	v_permlane32_swap_b32_e32 v85, v145
	v_permlane32_swap_b32_e32 v89, v146
	v_permlane32_swap_b32_e32 v93, v147
	v_add_f32_e32 v81, v81, v144
	v_add_f32_e32 v85, v85, v145
	v_add_f32_e32 v89, v89, v146
	v_add_f32_e32 v93, v93, v147
	v_fmamk_f32 v81, v81, 0x3c000000, v236
	v_fmamk_f32 v85, v85, 0x3c000000, v236
	v_fmamk_f32 v89, v89, 0x3c000000, v236
	v_fmamk_f32 v93, v93, 0x3c000000, v236
	v_mul_f32_e32 v144, 0x4b800000, v81
	v_mul_f32_e32 v145, 0x4b800000, v85
	v_mul_f32_e32 v146, 0x4b800000, v89
	v_mul_f32_e32 v147, 0x4b800000, v93
	v_cmp_gt_f32_e64 s[14:15], s7, v81
	v_cmp_gt_f32_e64 s[16:17], s7, v85
	v_cmp_gt_f32_e64 s[18:19], s7, v89
	v_cmp_gt_f32_e64 s[20:21], s7, v93
	v_cndmask_b32_e64 v81, v81, v144, s[14:15]
	v_cndmask_b32_e64 v85, v85, v145, s[16:17]
	v_cndmask_b32_e64 v89, v89, v146, s[18:19]
	v_cndmask_b32_e64 v93, v93, v147, s[20:21]
	v_rsq_f32_e32 v81, v81
	v_rsq_f32_e32 v85, v85
	v_rsq_f32_e32 v89, v89
	v_rsq_f32_e32 v93, v93
	v_mul_f32_e32 v144, 0x45800000, v81
	v_mul_f32_e32 v145, 0x45800000, v85
	v_mul_f32_e32 v146, 0x45800000, v89
	v_mul_f32_e32 v147, 0x45800000, v93
	v_cndmask_b32_e64 v81, v81, v144, s[14:15]
	v_cndmask_b32_e64 v85, v85, v145, s[16:17]
	v_cndmask_b32_e64 v89, v89, v146, s[18:19]
	v_cndmask_b32_e64 v93, v93, v147, s[20:21]
	v_mul_f32_e32 v81, v235, v81
	v_mul_f32_e32 v85, v235, v85
	v_mul_f32_e32 v89, v235, v89
	v_mul_f32_e32 v93, v235, v93
	v_mul_f32_e32 v79, v79, v81
	v_mul_f32_e32 v83, v83, v85
	v_mul_f32_e32 v87, v87, v89
	v_mul_f32_e32 v91, v91, v93
	v_mul_f32_e32 v78, v78, v81
	v_mul_f32_e32 v82, v82, v85
	v_mul_f32_e32 v86, v86, v89
	v_mul_f32_e32 v90, v90, v93
	v_mul_f32_e32 v79, v3, v79
	v_mul_f32_e32 v83, v3, v83
	v_mul_f32_e32 v87, v3, v87
	v_mul_f32_e32 v91, v3, v91
	v_mul_f32_e32 v78, v2, v78
	v_mul_f32_e32 v82, v2, v82
	v_mul_f32_e32 v86, v2, v86
	v_mul_f32_e32 v90, v2, v90
	v_mul_f32_e32 v106, v79, v106
	v_mul_f32_e32 v107, v83, v107
	v_mul_f32_e32 v108, v87, v108
	v_mul_f32_e32 v109, v91, v109
	v_mul_f32_e32 v78, v78, v80
	v_mul_f32_e32 v82, v82, v84
	v_mul_f32_e32 v86, v86, v88
	v_mul_f32_e32 v90, v90, v92
	v_cvt_pk_bf16_f32 v106, v78, v106
	v_cvt_pk_bf16_f32 v107, v82, v107
	v_cvt_pk_bf16_f32 v108, v86, v108
	v_cvt_pk_bf16_f32 v109, v90, v109
	s_nop 1
	s_mov_b64 vcc, s[22:23]
	v_cndmask_b32_dpp v148, v107, v106, vcc quad_perm:[1,0,3,2] row_mask:0xf bank_mask:0xf
	v_cndmask_b32_dpp v149, v109, v108, vcc quad_perm:[1,0,3,2] row_mask:0xf bank_mask:0xf
	s_mov_b64 vcc, s[24:25]
	v_cndmask_b32_dpp v150, v106, v107, vcc quad_perm:[1,0,3,2] row_mask:0xf bank_mask:0xf
	v_cndmask_b32_dpp v109, v108, v109, vcc quad_perm:[1,0,3,2] row_mask:0xf bank_mask:0xf
	s_mov_b64 vcc, s[26:27]
	v_cndmask_b32_dpp v106, v149, v148, vcc quad_perm:[2,3,0,1] row_mask:0xf bank_mask:0xf
	v_cndmask_b32_dpp v107, v109, v150, vcc quad_perm:[2,3,0,1] row_mask:0xf bank_mask:0xf
	s_mov_b64 vcc, s[30:31]
	v_cndmask_b32_dpp v108, v148, v149, vcc quad_perm:[2,3,0,1] row_mask:0xf bank_mask:0xf
	v_cndmask_b32_dpp v109, v150, v109, vcc quad_perm:[2,3,0,1] row_mask:0xf bank_mask:0xf
	global_store_dwordx4 v[140:141], v[106:109], off
	s_cmpk_eq_i32 s4, 0x4000
	s_cbranch_scc0 .Ldv2fin_loop
	v_readlane_b32 s4, v254, 4
	s_add_i32 s35, s35, s4
	s_movk_i32 s89, 0x3000
	s_movk_i32 s60, 0x1000
	s_cmp_ge_u32 s35, s34
	s_barrier
	s_cbranch_scc0 .LBB0_256
